# attention loop: priority raised at the loop head so the next-tile K/V global loads and the QK start issue at priority 1 (was raised only after the loads)
# speedup vs baseline: 1.0245x; 1.0006x over previous
; #define MFMA(a, b, c) __builtin_amdgcn_mfma_f32_32x32x16_bf16((a), (b), (c), 0, 0, 0)
; DI void flash_item64(const u16* Qbase  , int ntb, int ntw, const u16* Kbase, const u16* Vtbase,
;                      u16* Obase  , char* smem) {
;     ...
;   auto gload = [&](int t) {
; #pragma unroll
;     for (int i = 0; i < 3; i++) { int id = tid + 256 * i; int row = id / 12, ch = id % 12; rk[i] = *(const u32x4*)(Kbase + (long)(t * 64 + row) * 96 + ch * 8); }
; #pragma unroll
;     for (int i = 0; i < 2; i++) { int id = tid + 256 * i; int row = id >> 3, ch = id & 7; rv[i] = *(const u32x4*)(Vtbase + (long)row * LDVT + t * 64 + ch * 8); }
;   };
;     ...
; #pragma unroll
;     for (int sub = 0; sub < 2; sub++)
; #pragma unroll
;       for (int ks = 0; ks < KS; ks++) {
;         bf16x8 a = *(const bf16x8*)(cK + sub * 32 * LDK + ks * 16);
;         s[sub][0] = MFMA(a, qf[0][ks], s[sub][0]);
;         s[sub][1] = MFMA(a, qf[1][ks], s[sub][1]);
;       }
; #pragma unroll
;     for (int qh = 0; qh < 2; qh++) {
;       float mx = -1e30f;
; #pragma unroll
;       for (int sub = 0; sub < 2; sub++)
; #pragma unroll
;         for (int i = 0; i < 16; i++) mx = fmaxf(mx, s[sub][qh][i]);
;       mx = xhalf_max(mx);
.LBB0_846:
	s_setprio 1
	s_add_i32 s62, s4, 1
	s_cmp_lt_i32 s62, s61
	s_cselect_b64 s[24:25], -1, 0
	s_cmp_ge_i32 s62, s61
	s_cbranch_scc1 .LBB0_848
	v_add_u32_e32 v68, s6, v225
	v_mad_i64_i32 v[68:69], s[26:27], v68, s29, v[216:217]
	v_add_u32_e32 v70, s6, v226
	v_mad_i64_i32 v[70:71], s[26:27], v70, s29, v[218:219]
	global_load_dwordx4 v[180:183], v[68:69], off
	global_load_dwordx4 v[184:187], v[70:71], off
	v_add_u32_e32 v68, s6, v227
	v_mad_i64_i32 v[68:69], s[26:27], v68, s29, v[220:221]
	s_lshl_b64 s[26:27], s[6:7], 1
	s_nop 0
	v_lshl_add_u64 v[70:71], v[212:213], 0, s[26:27]
	global_load_dwordx4 v[188:191], v[68:69], off
	global_load_dwordx4 v[192:195], v[70:71], off
	v_lshl_add_u64 v[68:69], v[214:215], 0, s[26:27]
	global_load_dwordx4 v[196:199], v[68:69], off
.LBB0_848:
	v_cmp_le_i32_e32 vcc, s4, v233
	s_and_saveexec_b64 s[26:27], vcc
	s_cbranch_execz .LBB0_854
	s_and_b32 s63, s4, 1
	s_mul_i32 s4, s63, 0x3400
	v_add_u32_e32 v235, s4, v207
	v_or_b32_e32 v236, v234, v211
	v_cmp_ne_u32_e32 vcc, 0, v236
	s_cbranch_vccnz .Lqk_slow_1
	ds_read_b128 v[236:239], v235
	ds_read_b128 v[240:243], v235 offset:32
	ds_read_b128 v[244:247], v235 offset:64
	ds_read_b128 v[248:251], v235 offset:96
	s_waitcnt lgkmcnt(3)
	v_mfma_f32_32x32x16_bf16 v[116:131], v[236:239], v[132:135], 0
	v_mfma_f32_32x32x16_bf16 v[100:115], v[236:239], v[172:175], 0
	ds_read_b128 v[236:239], v235 offset:128
	s_waitcnt lgkmcnt(3)
	v_mfma_f32_32x32x16_bf16 v[116:131], v[240:243], v[136:139], v[116:131]
	v_mfma_f32_32x32x16_bf16 v[100:115], v[240:243], v[156:159], v[100:115]
	ds_read_b128 v[240:243], v235 offset:160
	s_waitcnt lgkmcnt(3)
	v_mfma_f32_32x32x16_bf16 v[116:131], v[244:247], v[140:143], v[116:131]
	v_mfma_f32_32x32x16_bf16 v[100:115], v[244:247], v[160:163], v[100:115]
	ds_read_b128 v[244:247], v235 offset:6656
	s_waitcnt lgkmcnt(3)
	v_mfma_f32_32x32x16_bf16 v[116:131], v[248:251], v[144:147], v[116:131]
	v_mfma_f32_32x32x16_bf16 v[100:115], v[248:251], v[164:167], v[100:115]
	ds_read_b128 v[248:251], v235 offset:6688
	s_waitcnt lgkmcnt(3)
	v_mfma_f32_32x32x16_bf16 v[116:131], v[236:239], v[148:151], v[116:131]
	v_mfma_f32_32x32x16_bf16 v[100:115], v[236:239], v[168:171], v[100:115]
	ds_read_b128 v[236:239], v235 offset:6720
	s_waitcnt lgkmcnt(3)
	v_mfma_f32_32x32x16_bf16 v[116:131], v[240:243], v[152:155], v[116:131]
	v_mfma_f32_32x32x16_bf16 v[100:115], v[240:243], v[176:179], v[100:115]
	ds_read_b128 v[240:243], v235 offset:6752
	s_waitcnt lgkmcnt(3)
	v_mfma_f32_32x32x16_bf16 v[84:99], v[244:247], v[132:135], 0
	v_mfma_f32_32x32x16_bf16 v[68:83], v[244:247], v[172:175], 0
	ds_read_b128 v[244:247], v235 offset:6784
	s_waitcnt lgkmcnt(3)
	v_mfma_f32_32x32x16_bf16 v[84:99], v[248:251], v[136:139], v[84:99]
	v_mfma_f32_32x32x16_bf16 v[68:83], v[248:251], v[156:159], v[68:83]
	ds_read_b128 v[248:251], v235 offset:6816
	s_waitcnt lgkmcnt(3)
	v_mfma_f32_32x32x16_bf16 v[84:99], v[236:239], v[140:143], v[84:99]
	v_max3_f32 v235, v116, s51, v117
	v_max3_f32 v235, v235, v118, v119
	v_mfma_f32_32x32x16_bf16 v[68:83], v[236:239], v[160:163], v[68:83]
	s_waitcnt lgkmcnt(2)
	v_mfma_f32_32x32x16_bf16 v[84:99], v[240:243], v[144:147], v[84:99]
	v_max3_f32 v235, v235, v120, v121
	v_max3_f32 v235, v235, v122, v123
	v_mfma_f32_32x32x16_bf16 v[68:83], v[240:243], v[164:167], v[68:83]
	s_waitcnt lgkmcnt(1)
	v_mfma_f32_32x32x16_bf16 v[84:99], v[244:247], v[148:151], v[84:99]
	v_max3_f32 v235, v235, v124, v125
	v_max3_f32 v235, v235, v126, v127
	v_mfma_f32_32x32x16_bf16 v[68:83], v[244:247], v[168:171], v[68:83]
	s_waitcnt lgkmcnt(0)
	v_mfma_f32_32x32x16_bf16 v[84:99], v[248:251], v[152:155], v[84:99]
	v_max3_f32 v235, v235, v128, v129
	v_max3_f32 v235, v235, v130, v131
	v_mfma_f32_32x32x16_bf16 v[68:83], v[248:251], v[176:179], v[68:83]
	s_nop 10
	v_max3_f32 v235, v235, v84, v85
	v_max3_f32 v235, v235, v86, v87
	v_max3_f32 v235, v235, v88, v89
	v_max3_f32 v235, v235, v90, v91
	v_max3_f32 v235, v235, v92, v93
	v_max3_f32 v235, v235, v94, v95
	v_max3_f32 v235, v235, v96, v97
	v_max3_f32 v235, v235, v98, v99
	s_branch .Lqk_join_1

; DI void flash_item64(const u16* Qbase  , int ntb, int ntw, const u16* Kbase, const u16* Vtbase,
;                      u16* Obase  , char* smem) {
;     ...
;   auto sstore = [&](int buf) {
; #pragma unroll
;     for (int i = 0; i < 3; i++) { int id = tid + 256 * i; int row = id / 12, ch = id % 12; *(u32x4*)(sK + buf * KTILE + row * LDK + ch * 8) = rk[i]; }
; #pragma unroll
;     for (int i = 0; i < 2; i++) { int id = tid + 256 * i; int row = id >> 3, ch = id & 7; *(u32x4*)(sV + buf * VTILE + row * LDV + ch * 8) = rv[i]; }
;   };
;     ...
;     if (t < ntw) { __builtin_amdgcn_s_setprio(1); compute(t & 1); __builtin_amdgcn_s_setprio(0); }
;     if (more) sstore((t + 1) & 1);
.LBB0_854:
	s_or_b64 exec, exec, s[26:27]
	s_setprio 0
	s_andn2_b64 vcc, exec, s[24:25]
	s_cbranch_vccnz .LBB0_856
	s_and_b32 s4, s62, 1
	s_mul_i32 s5, s4, 0x3400
	v_lshlrev_b32_e32 v68, 1, v228
	v_lshlrev_b32_e32 v69, 1, v206
	v_add3_u32 v68, s5, v68, v69
	s_waitcnt vmcnt(4)
	ds_write_b128 v68, v[180:183]
	v_lshlrev_b32_e32 v68, 1, v229
	v_lshlrev_b32_e32 v69, 1, v208
	v_add3_u32 v68, s5, v68, v69
	s_waitcnt vmcnt(3)
	ds_write_b128 v68, v[184:187]
	v_lshlrev_b32_e32 v68, 1, v230
	v_lshlrev_b32_e32 v69, 1, v210
	v_add3_u32 v68, s5, v68, v69
	s_lshl_b32 s4, s4, 12
	s_waitcnt vmcnt(2)
	ds_write_b128 v68, v[188:191]
	s_sub_i32 s4, s5, s4
	v_lshlrev_b32_e32 v68, 1, v231
	v_add3_u32 v68, s4, v68, v2
	s_waitcnt vmcnt(1)
	ds_write_b128 v68, v[192:195] offset:26624
	v_lshlrev_b32_e32 v68, 1, v232
	v_add3_u32 v68, s4, v68, v2
	s_waitcnt vmcnt(0)
	ds_write_b128 v68, v[196:199] offset:26624

; #define MFMA(a, b, c) __builtin_amdgcn_mfma_f32_32x32x16_bf16((a), (b), (c), 0, 0, 0)
; DI void flash_item64(const u16* Qbase  , int ntb, int ntw, const u16* Kbase, const u16* Vtbase,
;                      u16* Obase  , char* smem) {
;     ...
;   auto gload = [&](int t) {
; #pragma unroll
;     for (int i = 0; i < 3; i++) { int id = tid + 256 * i; int row = id / 12, ch = id % 12; rk[i] = *(const u32x4*)(Kbase + (long)(t * 64 + row) * 96 + ch * 8); }
; #pragma unroll
;     for (int i = 0; i < 2; i++) { int id = tid + 256 * i; int row = id >> 3, ch = id & 7; rv[i] = *(const u32x4*)(Vtbase + (long)row * LDVT + t * 64 + ch * 8); }
;   };
;     ...
; #pragma unroll
;     for (int sub = 0; sub < 2; sub++)
; #pragma unroll
;       for (int ks = 0; ks < KS; ks++) {
;         bf16x8 a = *(const bf16x8*)(cK + sub * 32 * LDK + ks * 16);
;         s[sub][0] = MFMA(a, qf[0][ks], s[sub][0]);
;         s[sub][1] = MFMA(a, qf[1][ks], s[sub][1]);
;       }
; #pragma unroll
;     for (int qh = 0; qh < 2; qh++) {
;       float mx = -1e30f;
; #pragma unroll
;       for (int sub = 0; sub < 2; sub++)
; #pragma unroll
;         for (int i = 0; i < 16; i++) mx = fmaxf(mx, s[sub][qh][i]);
;       mx = xhalf_max(mx);
.LBB0_2248:
	s_setprio 1
	s_add_i32 s60, s61, 1
	s_cmp_lt_i32 s60, s59
	s_cselect_b64 s[22:23], -1, 0
	s_cmp_ge_i32 s60, s59
	s_cbranch_scc1 .LBB0_2250
	v_add_u32_e32 v68, s4, v225
	v_mad_i64_i32 v[68:69], s[24:25], v68, s27, v[216:217]
	v_add_u32_e32 v70, s4, v226
	v_mad_i64_i32 v[70:71], s[24:25], v70, s27, v[218:219]
	global_load_dwordx4 v[180:183], v[68:69], off
	global_load_dwordx4 v[184:187], v[70:71], off
	v_add_u32_e32 v68, s4, v227
	v_mad_i64_i32 v[68:69], s[24:25], v68, s27, v[220:221]
	s_lshl_b64 s[24:25], s[4:5], 1
	s_nop 0
	v_lshl_add_u64 v[70:71], v[212:213], 0, s[24:25]
	global_load_dwordx4 v[188:191], v[68:69], off
	global_load_dwordx4 v[192:195], v[70:71], off
	v_lshl_add_u64 v[68:69], v[214:215], 0, s[24:25]
	global_load_dwordx4 v[196:199], v[68:69], off
.LBB0_2250:
	v_cmp_le_i32_e32 vcc, s61, v233
	s_and_saveexec_b64 s[24:25], vcc
	s_cbranch_execz .LBB0_2256
	s_and_b32 s61, s61, 1
	s_mul_i32 s62, s61, 0x3400
	v_add_u32_e32 v235, s62, v207
	v_or_b32_e32 v236, v234, v211
	v_cmp_ne_u32_e32 vcc, 0, v236
	s_cbranch_vccnz .Lqk_slow_2
	ds_read_b128 v[236:239], v235
	ds_read_b128 v[240:243], v235 offset:32
	ds_read_b128 v[244:247], v235 offset:64
	ds_read_b128 v[248:251], v235 offset:96
	s_waitcnt lgkmcnt(3)
	v_mfma_f32_32x32x16_bf16 v[116:131], v[236:239], v[132:135], 0
	v_mfma_f32_32x32x16_bf16 v[100:115], v[236:239], v[172:175], 0
	ds_read_b128 v[236:239], v235 offset:128
	s_waitcnt lgkmcnt(3)
	v_mfma_f32_32x32x16_bf16 v[116:131], v[240:243], v[136:139], v[116:131]
	v_mfma_f32_32x32x16_bf16 v[100:115], v[240:243], v[156:159], v[100:115]
	ds_read_b128 v[240:243], v235 offset:160
	s_waitcnt lgkmcnt(3)
	v_mfma_f32_32x32x16_bf16 v[116:131], v[244:247], v[140:143], v[116:131]
	v_mfma_f32_32x32x16_bf16 v[100:115], v[244:247], v[160:163], v[100:115]
	ds_read_b128 v[244:247], v235 offset:6656
	s_waitcnt lgkmcnt(3)
	v_mfma_f32_32x32x16_bf16 v[116:131], v[248:251], v[144:147], v[116:131]
	v_mfma_f32_32x32x16_bf16 v[100:115], v[248:251], v[164:167], v[100:115]
	ds_read_b128 v[248:251], v235 offset:6688
	s_waitcnt lgkmcnt(3)
	v_mfma_f32_32x32x16_bf16 v[116:131], v[236:239], v[148:151], v[116:131]
	v_mfma_f32_32x32x16_bf16 v[100:115], v[236:239], v[168:171], v[100:115]
	ds_read_b128 v[236:239], v235 offset:6720
	s_waitcnt lgkmcnt(3)
	v_mfma_f32_32x32x16_bf16 v[116:131], v[240:243], v[152:155], v[116:131]
	v_mfma_f32_32x32x16_bf16 v[100:115], v[240:243], v[176:179], v[100:115]
	ds_read_b128 v[240:243], v235 offset:6752
	s_waitcnt lgkmcnt(3)
	v_mfma_f32_32x32x16_bf16 v[84:99], v[244:247], v[132:135], 0
	v_mfma_f32_32x32x16_bf16 v[68:83], v[244:247], v[172:175], 0
	ds_read_b128 v[244:247], v235 offset:6784
	s_waitcnt lgkmcnt(3)
	v_mfma_f32_32x32x16_bf16 v[84:99], v[248:251], v[136:139], v[84:99]
	v_mfma_f32_32x32x16_bf16 v[68:83], v[248:251], v[156:159], v[68:83]
	ds_read_b128 v[248:251], v235 offset:6816
	s_waitcnt lgkmcnt(3)
	v_mfma_f32_32x32x16_bf16 v[84:99], v[236:239], v[140:143], v[84:99]
	v_max3_f32 v235, v116, s49, v117
	v_max3_f32 v235, v235, v118, v119
	v_mfma_f32_32x32x16_bf16 v[68:83], v[236:239], v[160:163], v[68:83]
	s_waitcnt lgkmcnt(2)
	v_mfma_f32_32x32x16_bf16 v[84:99], v[240:243], v[144:147], v[84:99]
	v_max3_f32 v235, v235, v120, v121
	v_max3_f32 v235, v235, v122, v123
	v_mfma_f32_32x32x16_bf16 v[68:83], v[240:243], v[164:167], v[68:83]
	s_waitcnt lgkmcnt(1)
	v_mfma_f32_32x32x16_bf16 v[84:99], v[244:247], v[148:151], v[84:99]
	v_max3_f32 v235, v235, v124, v125
	v_max3_f32 v235, v235, v126, v127
	v_mfma_f32_32x32x16_bf16 v[68:83], v[244:247], v[168:171], v[68:83]
	s_waitcnt lgkmcnt(0)
	v_mfma_f32_32x32x16_bf16 v[84:99], v[248:251], v[152:155], v[84:99]
	v_max3_f32 v235, v235, v128, v129
	v_max3_f32 v235, v235, v130, v131
	v_mfma_f32_32x32x16_bf16 v[68:83], v[248:251], v[176:179], v[68:83]
	s_nop 10
	v_max3_f32 v235, v235, v84, v85
	v_max3_f32 v235, v235, v86, v87
	v_max3_f32 v235, v235, v88, v89
	v_max3_f32 v235, v235, v90, v91
	v_max3_f32 v235, v235, v92, v93
	v_max3_f32 v235, v235, v94, v95
	v_max3_f32 v235, v235, v96, v97
	v_max3_f32 v235, v235, v98, v99
	s_branch .Lqk_join_2

; DI void flash_item64(const u16* Qbase  , int ntb, int ntw, const u16* Kbase, const u16* Vtbase,
;                      u16* Obase  , char* smem) {
;     ...
;   auto sstore = [&](int buf) {
; #pragma unroll
;     for (int i = 0; i < 3; i++) { int id = tid + 256 * i; int row = id / 12, ch = id % 12; *(u32x4*)(sK + buf * KTILE + row * LDK + ch * 8) = rk[i]; }
; #pragma unroll
;     for (int i = 0; i < 2; i++) { int id = tid + 256 * i; int row = id >> 3, ch = id & 7; *(u32x4*)(sV + buf * VTILE + row * LDV + ch * 8) = rv[i]; }
;   };
;     ...
;     if (t < ntw) { __builtin_amdgcn_s_setprio(1); compute(t & 1); __builtin_amdgcn_s_setprio(0); }
;     if (more) sstore((t + 1) & 1);
.LBB0_2256:
	s_or_b64 exec, exec, s[24:25]
	s_setprio 0
	s_andn2_b64 vcc, exec, s[22:23]
	s_cbranch_vccnz .LBB0_2258
	s_and_b32 s22, s60, 1
	s_mul_i32 s23, s22, 0x3400
	v_lshlrev_b32_e32 v68, 1, v228
	v_lshlrev_b32_e32 v69, 1, v206
	v_add3_u32 v68, s23, v68, v69
	s_waitcnt vmcnt(4)
	ds_write_b128 v68, v[180:183]
	v_lshlrev_b32_e32 v68, 1, v229
	v_lshlrev_b32_e32 v69, 1, v208
	v_add3_u32 v68, s23, v68, v69
	s_waitcnt vmcnt(3)
	ds_write_b128 v68, v[184:187]
	v_lshlrev_b32_e32 v68, 1, v230
	v_lshlrev_b32_e32 v69, 1, v210
	v_add3_u32 v68, s23, v68, v69
	s_lshl_b32 s22, s22, 12
	s_waitcnt vmcnt(2)
	ds_write_b128 v68, v[188:191]
	s_sub_i32 s22, s23, s22
	v_lshlrev_b32_e32 v68, 1, v231
	v_add3_u32 v68, s22, v68, v2
	s_waitcnt vmcnt(1)
	ds_write_b128 v68, v[192:195] offset:26624
	v_lshlrev_b32_e32 v68, 1, v232
	v_add3_u32 v68, s22, v68, v2
	s_waitcnt vmcnt(0)
	ds_write_b128 v68, v[196:199] offset:26624
